# P9 conv epilogue v3: each thread walks 8 consecutive rows with the two previous rows kept unpacked in registers (10 instead of 16 staged-row reads and unpacks per 8 output rows)
# speedup vs baseline: 1.0161x; 1.0015x over previous
.LBB0_1036:
	v_mov_b32_e32 v130, v191
	s_waitcnt vmcnt(0)
	s_barrier
	v_lshl_or_b32 v216, s0, 7, v142
	v_lshlrev_b32_e32 v216, 2, v216
	v_add_u32_e32 v217, 0x2c00, v216
	global_load_dwordx4 v[148:151], v216, s[16:17]
	global_load_dwordx4 v[152:155], v216, s[16:17] offset:16
	global_load_dwordx4 v[180:183], v217, s[16:17]
	global_load_dwordx4 v[184:187], v217, s[16:17] offset:16
	global_load_dwordx4 v[156:159], v216, s[8:9]
	global_load_dwordx4 v[160:163], v216, s[8:9] offset:16
	global_load_dwordx4 v[192:195], v217, s[8:9]
	global_load_dwordx4 v[196:199], v217, s[8:9] offset:16
	global_load_dwordx4 v[164:167], v216, s[20:21]
	global_load_dwordx4 v[168:171], v216, s[20:21] offset:16
	global_load_dwordx4 v[200:203], v217, s[20:21]
	global_load_dwordx4 v[204:207], v217, s[20:21] offset:16
	global_load_dwordx4 v[172:175], v216, s[18:19]
	global_load_dwordx4 v[176:179], v216, s[18:19] offset:16
	global_load_dwordx4 v[208:211], v217, s[18:19]
	global_load_dwordx4 v[212:215], v217, s[18:19] offset:16
	s_lshl_b32 s1, s1, 6
	v_and_or_b32 v132, v130, 15, s61
	v_and_b32_e32 v130, 48, v130
	s_add_i32 s1, s1, 0
	v_mul_lo_u32 v132, v132, s50
	v_add3_u32 v130, s1, v130, v132
	v_cvt_pk_bf16_f32 v68, v68, v69
	v_cvt_pk_bf16_f32 v69, v70, v71
	v_cvt_pk_bf16_f32 v70, v64, v65
	v_add_u32_e32 v64, 0x10800, v130
	v_cvt_pk_bf16_f32 v60, v60, v61
	v_cvt_pk_bf16_f32 v61, v62, v63
	v_cvt_pk_bf16_f32 v62, v56, v57
	v_cvt_pk_bf16_f32 v63, v58, v59
	ds_write_b128 v64, v[60:63]
	v_cvt_pk_bf16_f32 v52, v52, v53
	v_cvt_pk_bf16_f32 v53, v54, v55
	v_cvt_pk_bf16_f32 v54, v48, v49
	v_cvt_pk_bf16_f32 v55, v50, v51
	v_add_u32_e32 v48, 0x10900, v130
	v_cvt_pk_bf16_f32 v36, v36, v37
	v_cvt_pk_bf16_f32 v37, v38, v39
	v_cvt_pk_bf16_f32 v38, v32, v33
	v_cvt_pk_bf16_f32 v39, v34, v35
	v_add_u32_e32 v32, 0x12a00, v130
	v_cvt_pk_bf16_f32 v20, v20, v21
	v_cvt_pk_bf16_f32 v21, v22, v23
	v_cvt_pk_bf16_f32 v22, v16, v17
	v_cvt_pk_bf16_f32 v23, v18, v19
	v_add_u32_e32 v16, 0x14b00, v130
	v_lshl_or_b32 v64, s0, 7, v142
	v_cvt_pk_bf16_f32 v124, v124, v125
	v_cvt_pk_bf16_f32 v125, v126, v127
	v_cvt_pk_bf16_f32 v126, v120, v121
	v_cvt_pk_bf16_f32 v127, v122, v123
	v_cvt_pk_bf16_f32 v116, v116, v117
	v_cvt_pk_bf16_f32 v117, v118, v119
	v_cvt_pk_bf16_f32 v118, v112, v113
	v_cvt_pk_bf16_f32 v119, v114, v115
	v_cvt_pk_bf16_f32 v108, v108, v109
	v_cvt_pk_bf16_f32 v109, v110, v111
	v_cvt_pk_bf16_f32 v110, v104, v105
	v_cvt_pk_bf16_f32 v111, v106, v107
	v_cvt_pk_bf16_f32 v100, v100, v101
	v_cvt_pk_bf16_f32 v101, v102, v103
	v_cvt_pk_bf16_f32 v102, v96, v97
	v_cvt_pk_bf16_f32 v103, v98, v99
	v_cvt_pk_bf16_f32 v92, v92, v93
	v_cvt_pk_bf16_f32 v93, v94, v95
	v_cvt_pk_bf16_f32 v94, v88, v89
	v_cvt_pk_bf16_f32 v95, v90, v91
	v_cvt_pk_bf16_f32 v84, v84, v85
	v_cvt_pk_bf16_f32 v85, v86, v87
	v_cvt_pk_bf16_f32 v86, v80, v81
	v_cvt_pk_bf16_f32 v87, v82, v83
	v_cvt_pk_bf16_f32 v76, v76, v77
	v_cvt_pk_bf16_f32 v77, v78, v79
	v_cvt_pk_bf16_f32 v78, v72, v73
	v_cvt_pk_bf16_f32 v79, v74, v75
	v_cvt_pk_bf16_f32 v71, v66, v67
	ds_write_b128 v48, v[52:55]
	v_add_u32_e32 v48, 0x12900, v130
	v_cvt_pk_bf16_f32 v44, v44, v45
	v_cvt_pk_bf16_f32 v45, v46, v47
	v_cvt_pk_bf16_f32 v46, v40, v41
	v_cvt_pk_bf16_f32 v47, v42, v43
	ds_write_b128 v32, v[36:39]
	v_add_u32_e32 v32, 0x14a00, v130
	v_cvt_pk_bf16_f32 v28, v28, v29
	v_cvt_pk_bf16_f32 v29, v30, v31
	v_cvt_pk_bf16_f32 v30, v24, v25
	v_cvt_pk_bf16_f32 v31, v26, v27
	ds_write_b128 v16, v[20:23]
	v_add_u32_e32 v16, 0x16b00, v130
	v_cvt_pk_bf16_f32 v12, v12, v13
	v_cvt_pk_bf16_f32 v13, v14, v15
	v_cvt_pk_bf16_f32 v14, v8, v9
	v_cvt_pk_bf16_f32 v15, v10, v11
	v_cvt_pk_bf16_f32 v4, v4, v5
	v_cvt_pk_bf16_f32 v5, v6, v7
	v_cvt_pk_bf16_f32 v6, v0, v1
	v_cvt_pk_bf16_f32 v7, v2, v3
	v_add_u32_e32 v0, 0x16c00, v130
	v_ashrrev_i32_e32 v65, 31, v64
	ds_write_b128 v130, v[124:127]
	ds_write_b128 v130, v[116:119] offset:256
	ds_write_b128 v130, v[108:111] offset:8448
	ds_write_b128 v130, v[100:103] offset:8704
	ds_write_b128 v130, v[92:95] offset:16896
	ds_write_b128 v130, v[84:87] offset:17152
	ds_write_b128 v130, v[76:79] offset:25344
	ds_write_b128 v130, v[68:71] offset:25600
	ds_write_b128 v48, v[44:47]
	ds_write_b128 v32, v[28:31]
	ds_write_b128 v16, v[12:15]
	ds_write_b128 v0, v[4:7]
	s_waitcnt lgkmcnt(0)
	s_barrier
	s_mulk_i32 s57, 0xfe
	s_mulk_i32 s59, 0xfe
	s_sub_i32 s0, s57, s59
	s_mul_i32 s58, s58, 0xa6b0
	s_sub_i32 s10, s0, s58
	v_lshl_add_u64 v[64:65], v[64:65], 1, s[14:15]
	s_add_i32 s10, s10, -2
	s_movk_i32 s11, 0xfbe0
	v_lshlrev_b32_e32 v66, 3, v143
	v_mul_u32_u24_e32 v223, 0xe70, v143
	v_add_u32_e32 v223, v223, v144
	v_add_u32_e32 v222, 0xfffffbe0, v223
	v_mov_b32_e32 v218, 0xbdd2d3e7
	v_mov_b32_e32 v219, 0xbdd2d3e7
	v_mov_b32_e32 v220, 0xc0135761
	v_mov_b32_e32 v221, 0xc0135761
	ds_read_b128 v[68:71], v222
	ds_read_b128 v[72:75], v222 offset:528
	ds_read_b128 v[84:87], v222 offset:256
	ds_read_b128 v[88:91], v222 offset:784
	s_waitcnt vmcnt(0) lgkmcnt(0)
	v_lshlrev_b32_e32 v0, 16, v68
	v_and_b32_e32 v1, 0xffff0000, v68
	v_lshlrev_b32_e32 v2, 16, v69
	v_and_b32_e32 v3, 0xffff0000, v69
	v_lshlrev_b32_e32 v4, 16, v70
	v_and_b32_e32 v5, 0xffff0000, v70
	v_lshlrev_b32_e32 v6, 16, v71
	v_and_b32_e32 v7, 0xffff0000, v71
	v_lshlrev_b32_e32 v8, 16, v72
	v_and_b32_e32 v9, 0xffff0000, v72
	v_lshlrev_b32_e32 v10, 16, v73
	v_and_b32_e32 v11, 0xffff0000, v73
	v_lshlrev_b32_e32 v12, 16, v74
	v_and_b32_e32 v13, 0xffff0000, v74
	v_lshlrev_b32_e32 v14, 16, v75
	v_and_b32_e32 v15, 0xffff0000, v75
	v_lshlrev_b32_e32 v32, 16, v84
	v_and_b32_e32 v33, 0xffff0000, v84
	v_lshlrev_b32_e32 v34, 16, v85
	v_and_b32_e32 v35, 0xffff0000, v85
	v_lshlrev_b32_e32 v36, 16, v86
	v_and_b32_e32 v37, 0xffff0000, v86
	v_lshlrev_b32_e32 v38, 16, v87
	v_and_b32_e32 v39, 0xffff0000, v87
	v_lshlrev_b32_e32 v40, 16, v88
	v_and_b32_e32 v41, 0xffff0000, v88
	v_lshlrev_b32_e32 v42, 16, v89
	v_and_b32_e32 v43, 0xffff0000, v89
	v_lshlrev_b32_e32 v44, 16, v90
	v_and_b32_e32 v45, 0xffff0000, v90
	v_lshlrev_b32_e32 v46, 16, v91
	v_and_b32_e32 v47, 0xffff0000, v91
	s_mov_b32 s11, 0
.Lc3_loop:
	ds_read_b128 v[68:71], v222 offset:1056
	ds_read_b128 v[72:75], v222 offset:1584
	ds_read_b128 v[84:87], v222 offset:1312
	ds_read_b128 v[88:91], v222 offset:1840
	v_add_u32_e32 v67, s10, v66
	v_cmp_lt_u32_e32 vcc, 1, v66
	v_cmp_gt_i32_e64 s[0:1], s54, v67
	s_and_b64 s[0:1], vcc, s[0:1]
	v_and_b32_e32 v116, 0xfff, v67
	s_waitcnt lgkmcnt(2)
	v_lshlrev_b32_e32 v16, 16, v68
	v_and_b32_e32 v17, 0xffff0000, v68
	v_lshlrev_b32_e32 v18, 16, v69
	v_and_b32_e32 v19, 0xffff0000, v69
	v_lshlrev_b32_e32 v20, 16, v70
	v_and_b32_e32 v21, 0xffff0000, v70
	v_lshlrev_b32_e32 v22, 16, v71
	v_and_b32_e32 v23, 0xffff0000, v71
	v_lshlrev_b32_e32 v24, 16, v72
	v_and_b32_e32 v25, 0xffff0000, v72
	v_lshlrev_b32_e32 v26, 16, v73
	v_and_b32_e32 v27, 0xffff0000, v73
	v_lshlrev_b32_e32 v28, 16, v74
	v_and_b32_e32 v29, 0xffff0000, v74
	v_lshlrev_b32_e32 v30, 16, v75
	v_and_b32_e32 v31, 0xffff0000, v75
	s_waitcnt lgkmcnt(0)
	v_lshlrev_b32_e32 v48, 16, v84
	v_and_b32_e32 v49, 0xffff0000, v84
	v_lshlrev_b32_e32 v50, 16, v85
	v_and_b32_e32 v51, 0xffff0000, v85
	v_lshlrev_b32_e32 v52, 16, v86
	v_and_b32_e32 v53, 0xffff0000, v86
	v_lshlrev_b32_e32 v54, 16, v87
	v_and_b32_e32 v55, 0xffff0000, v87
	v_lshlrev_b32_e32 v56, 16, v88
	v_and_b32_e32 v57, 0xffff0000, v88
	v_lshlrev_b32_e32 v58, 16, v89
	v_and_b32_e32 v59, 0xffff0000, v89
	v_lshlrev_b32_e32 v60, 16, v90
	v_and_b32_e32 v61, 0xffff0000, v90
	v_lshlrev_b32_e32 v62, 16, v91
	v_and_b32_e32 v63, 0xffff0000, v91
	v_cmp_eq_u32_e32 vcc, 0, v116
	s_cbranch_vccz .Lc3_commonA
	v_cmp_ne_u32_e32 vcc, 0, v116
	s_nop 1
	v_cndmask_b32_e32 v0, 0, v0, vcc
	v_cndmask_b32_e32 v1, 0, v1, vcc
	v_cndmask_b32_e32 v2, 0, v2, vcc
	v_cndmask_b32_e32 v3, 0, v3, vcc
	v_cndmask_b32_e32 v4, 0, v4, vcc
	v_cndmask_b32_e32 v5, 0, v5, vcc
	v_cndmask_b32_e32 v6, 0, v6, vcc
	v_cndmask_b32_e32 v7, 0, v7, vcc
	v_cndmask_b32_e32 v8, 0, v8, vcc
	v_cndmask_b32_e32 v9, 0, v9, vcc
	v_cndmask_b32_e32 v10, 0, v10, vcc
	v_cndmask_b32_e32 v11, 0, v11, vcc
	v_cndmask_b32_e32 v12, 0, v12, vcc
	v_cndmask_b32_e32 v13, 0, v13, vcc
	v_cndmask_b32_e32 v14, 0, v14, vcc
	v_cndmask_b32_e32 v15, 0, v15, vcc
	v_cndmask_b32_e32 v32, 0, v32, vcc
	v_cndmask_b32_e32 v33, 0, v33, vcc
	v_cndmask_b32_e32 v34, 0, v34, vcc
	v_cndmask_b32_e32 v35, 0, v35, vcc
	v_cndmask_b32_e32 v36, 0, v36, vcc
	v_cndmask_b32_e32 v37, 0, v37, vcc
	v_cndmask_b32_e32 v38, 0, v38, vcc
	v_cndmask_b32_e32 v39, 0, v39, vcc
	v_cndmask_b32_e32 v40, 0, v40, vcc
	v_cndmask_b32_e32 v41, 0, v41, vcc
	v_cndmask_b32_e32 v42, 0, v42, vcc
	v_cndmask_b32_e32 v43, 0, v43, vcc
	v_cndmask_b32_e32 v44, 0, v44, vcc
	v_cndmask_b32_e32 v45, 0, v45, vcc
	v_cndmask_b32_e32 v46, 0, v46, vcc
	v_cndmask_b32_e32 v47, 0, v47, vcc
.Lc3_commonA:
	v_pk_fma_f32 v[68:69], v[164:165], v[16:17], v[172:173]
	v_pk_fma_f32 v[70:71], v[166:167], v[18:19], v[174:175]
	v_pk_fma_f32 v[72:73], v[168:169], v[20:21], v[176:177]
	v_pk_fma_f32 v[74:75], v[170:171], v[22:23], v[178:179]
	v_pk_fma_f32 v[68:69], v[156:157], v[8:9], v[68:69]
	v_pk_fma_f32 v[70:71], v[158:159], v[10:11], v[70:71]
	v_pk_fma_f32 v[72:73], v[160:161], v[12:13], v[72:73]
	v_pk_fma_f32 v[74:75], v[162:163], v[14:15], v[74:75]
	v_pk_fma_f32 v[68:69], v[148:149], v[0:1], v[68:69]
	v_pk_fma_f32 v[70:71], v[150:151], v[2:3], v[70:71]
	v_pk_fma_f32 v[72:73], v[152:153], v[4:5], v[72:73]
	v_pk_fma_f32 v[74:75], v[154:155], v[6:7], v[74:75]
	v_pk_fma_f32 v[76:77], v[164:165], v[24:25], v[172:173]
	v_pk_fma_f32 v[78:79], v[166:167], v[26:27], v[174:175]
	v_pk_fma_f32 v[80:81], v[168:169], v[28:29], v[176:177]
	v_pk_fma_f32 v[82:83], v[170:171], v[30:31], v[178:179]
	v_pk_fma_f32 v[76:77], v[156:157], v[16:17], v[76:77]
	v_pk_fma_f32 v[78:79], v[158:159], v[18:19], v[78:79]
	v_pk_fma_f32 v[80:81], v[160:161], v[20:21], v[80:81]
	v_pk_fma_f32 v[82:83], v[162:163], v[22:23], v[82:83]
	v_pk_fma_f32 v[76:77], v[148:149], v[8:9], v[76:77]
	v_pk_fma_f32 v[78:79], v[150:151], v[10:11], v[78:79]
	v_pk_fma_f32 v[80:81], v[152:153], v[12:13], v[80:81]
	v_pk_fma_f32 v[82:83], v[154:155], v[14:15], v[82:83]
	v_pk_mul_f32 v[100:101], v[68:69], v[68:69]
	v_pk_mul_f32 v[102:103], v[70:71], v[70:71]
	v_pk_mul_f32 v[104:105], v[72:73], v[72:73]
	v_pk_mul_f32 v[106:107], v[74:75], v[74:75]
	v_pk_mul_f32 v[108:109], v[76:77], v[76:77]
	v_pk_mul_f32 v[110:111], v[78:79], v[78:79]
	v_pk_mul_f32 v[112:113], v[80:81], v[80:81]
	v_pk_mul_f32 v[114:115], v[82:83], v[82:83]
	v_pk_fma_f32 v[100:101], v[100:101], v[218:219], v[220:221]
	v_pk_fma_f32 v[102:103], v[102:103], v[218:219], v[220:221]
	v_pk_fma_f32 v[104:105], v[104:105], v[218:219], v[220:221]
	v_pk_fma_f32 v[106:107], v[106:107], v[218:219], v[220:221]
	v_pk_fma_f32 v[108:109], v[108:109], v[218:219], v[220:221]
	v_pk_fma_f32 v[110:111], v[110:111], v[218:219], v[220:221]
	v_pk_fma_f32 v[112:113], v[112:113], v[218:219], v[220:221]
	v_pk_fma_f32 v[114:115], v[114:115], v[218:219], v[220:221]
	v_pk_mul_f32 v[100:101], v[68:69], v[100:101]
	v_pk_mul_f32 v[102:103], v[70:71], v[102:103]
	v_pk_mul_f32 v[104:105], v[72:73], v[104:105]
	v_pk_mul_f32 v[106:107], v[74:75], v[106:107]
	v_pk_mul_f32 v[108:109], v[76:77], v[108:109]
	v_pk_mul_f32 v[110:111], v[78:79], v[110:111]
	v_pk_mul_f32 v[112:113], v[80:81], v[112:113]
	v_pk_mul_f32 v[114:115], v[82:83], v[114:115]
	v_exp_f32_e32 v100, v100
	v_exp_f32_e32 v101, v101
	v_exp_f32_e32 v102, v102
	v_exp_f32_e32 v103, v103
	v_exp_f32_e32 v104, v104
	v_exp_f32_e32 v105, v105
	v_exp_f32_e32 v106, v106
	v_exp_f32_e32 v107, v107
	v_exp_f32_e32 v108, v108
	v_exp_f32_e32 v109, v109
	v_exp_f32_e32 v110, v110
	v_exp_f32_e32 v111, v111
	v_exp_f32_e32 v112, v112
	v_exp_f32_e32 v113, v113
	v_exp_f32_e32 v114, v114
	v_exp_f32_e32 v115, v115
	v_pk_fma_f32 v[84:85], v[200:201], v[48:49], v[208:209]
	v_pk_fma_f32 v[86:87], v[202:203], v[50:51], v[210:211]
	v_pk_fma_f32 v[88:89], v[204:205], v[52:53], v[212:213]
	v_pk_fma_f32 v[90:91], v[206:207], v[54:55], v[214:215]
	v_pk_fma_f32 v[84:85], v[192:193], v[40:41], v[84:85]
	v_pk_fma_f32 v[86:87], v[194:195], v[42:43], v[86:87]
	v_pk_fma_f32 v[88:89], v[196:197], v[44:45], v[88:89]
	v_pk_fma_f32 v[90:91], v[198:199], v[46:47], v[90:91]
	v_pk_fma_f32 v[84:85], v[180:181], v[32:33], v[84:85]
	v_pk_fma_f32 v[86:87], v[182:183], v[34:35], v[86:87]
	v_pk_fma_f32 v[88:89], v[184:185], v[36:37], v[88:89]
	v_pk_fma_f32 v[90:91], v[186:187], v[38:39], v[90:91]
	v_pk_fma_f32 v[92:93], v[200:201], v[56:57], v[208:209]
	v_pk_fma_f32 v[94:95], v[202:203], v[58:59], v[210:211]
	v_pk_fma_f32 v[96:97], v[204:205], v[60:61], v[212:213]
	v_pk_fma_f32 v[98:99], v[206:207], v[62:63], v[214:215]
	v_pk_fma_f32 v[92:93], v[192:193], v[48:49], v[92:93]
	v_pk_fma_f32 v[94:95], v[194:195], v[50:51], v[94:95]
	v_pk_fma_f32 v[96:97], v[196:197], v[52:53], v[96:97]
	v_pk_fma_f32 v[98:99], v[198:199], v[54:55], v[98:99]
	v_pk_fma_f32 v[92:93], v[180:181], v[40:41], v[92:93]
	v_pk_fma_f32 v[94:95], v[182:183], v[42:43], v[94:95]
	v_pk_fma_f32 v[96:97], v[184:185], v[44:45], v[96:97]
	v_pk_fma_f32 v[98:99], v[186:187], v[46:47], v[98:99]
	v_pk_add_f32 v[100:101], v[100:101], 1.0 op_sel_hi:[1,0]
	v_pk_add_f32 v[102:103], v[102:103], 1.0 op_sel_hi:[1,0]
	v_pk_add_f32 v[104:105], v[104:105], 1.0 op_sel_hi:[1,0]
	v_pk_add_f32 v[106:107], v[106:107], 1.0 op_sel_hi:[1,0]
	v_pk_add_f32 v[108:109], v[108:109], 1.0 op_sel_hi:[1,0]
	v_pk_add_f32 v[110:111], v[110:111], 1.0 op_sel_hi:[1,0]
	v_pk_add_f32 v[112:113], v[112:113], 1.0 op_sel_hi:[1,0]
	v_pk_add_f32 v[114:115], v[114:115], 1.0 op_sel_hi:[1,0]
	v_rcp_f32_e32 v100, v100
	v_rcp_f32_e32 v101, v101
	v_rcp_f32_e32 v102, v102
	v_rcp_f32_e32 v103, v103
	v_rcp_f32_e32 v104, v104
	v_rcp_f32_e32 v105, v105
	v_rcp_f32_e32 v106, v106
	v_rcp_f32_e32 v107, v107
	v_rcp_f32_e32 v108, v108
	v_rcp_f32_e32 v109, v109
	v_rcp_f32_e32 v110, v110
	v_rcp_f32_e32 v111, v111
	v_rcp_f32_e32 v112, v112
	v_rcp_f32_e32 v113, v113
	v_rcp_f32_e32 v114, v114
	v_rcp_f32_e32 v115, v115
	v_add_u32_e32 v117, 1, v67
	v_mad_i64_i32 v[124:125], s[4:5], v67, s56, v[64:65]
	v_mad_i64_i32 v[126:127], s[4:5], v117, s56, v[64:65]
	v_pk_mul_f32 v[68:69], v[68:69], v[100:101]
	v_pk_mul_f32 v[70:71], v[70:71], v[102:103]
	v_pk_mul_f32 v[72:73], v[72:73], v[104:105]
	v_pk_mul_f32 v[74:75], v[74:75], v[106:107]
	v_pk_mul_f32 v[76:77], v[76:77], v[108:109]
	v_pk_mul_f32 v[78:79], v[78:79], v[110:111]
	v_pk_mul_f32 v[80:81], v[80:81], v[112:113]
	v_pk_mul_f32 v[82:83], v[82:83], v[114:115]
	v_pk_mul_f32 v[68:69], v[68:69], v[84:85]
	v_pk_mul_f32 v[70:71], v[70:71], v[86:87]
	v_pk_mul_f32 v[72:73], v[72:73], v[88:89]
	v_pk_mul_f32 v[74:75], v[74:75], v[90:91]
	v_pk_mul_f32 v[76:77], v[76:77], v[92:93]
	v_pk_mul_f32 v[78:79], v[78:79], v[94:95]
	v_pk_mul_f32 v[80:81], v[80:81], v[96:97]
	v_pk_mul_f32 v[82:83], v[82:83], v[98:99]
	v_cvt_pk_bf16_f32 v116, v68, v69
	v_cvt_pk_bf16_f32 v117, v70, v71
	v_cvt_pk_bf16_f32 v118, v72, v73
	v_cvt_pk_bf16_f32 v119, v74, v75
	v_cvt_pk_bf16_f32 v120, v76, v77
	v_cvt_pk_bf16_f32 v121, v78, v79
	v_cvt_pk_bf16_f32 v122, v80, v81
	v_cvt_pk_bf16_f32 v123, v82, v83
	s_mov_b64 s[4:5], exec
	s_and_b64 exec, exec, s[0:1]
	global_store_dwordx4 v[124:125], v[116:119], off
	global_store_dwordx4 v[126:127], v[120:123], off
	s_mov_b64 exec, s[4:5]
	v_add_u32_e32 v66, 2, v66
	ds_read_b128 v[68:71], v222 offset:2112
	ds_read_b128 v[72:75], v222 offset:2640
	ds_read_b128 v[84:87], v222 offset:2368
	ds_read_b128 v[88:91], v222 offset:2896
	v_add_u32_e32 v67, s10, v66
	v_cmp_lt_u32_e32 vcc, 1, v66
	v_cmp_gt_i32_e64 s[0:1], s54, v67
	s_and_b64 s[0:1], vcc, s[0:1]
	v_and_b32_e32 v116, 0xfff, v67
	s_waitcnt lgkmcnt(2)
	v_lshlrev_b32_e32 v0, 16, v68
	v_and_b32_e32 v1, 0xffff0000, v68
	v_lshlrev_b32_e32 v2, 16, v69
	v_and_b32_e32 v3, 0xffff0000, v69
	v_lshlrev_b32_e32 v4, 16, v70
	v_and_b32_e32 v5, 0xffff0000, v70
	v_lshlrev_b32_e32 v6, 16, v71
	v_and_b32_e32 v7, 0xffff0000, v71
	v_lshlrev_b32_e32 v8, 16, v72
	v_and_b32_e32 v9, 0xffff0000, v72
	v_lshlrev_b32_e32 v10, 16, v73
	v_and_b32_e32 v11, 0xffff0000, v73
	v_lshlrev_b32_e32 v12, 16, v74
	v_and_b32_e32 v13, 0xffff0000, v74
	v_lshlrev_b32_e32 v14, 16, v75
	v_and_b32_e32 v15, 0xffff0000, v75
	s_waitcnt lgkmcnt(0)
	v_lshlrev_b32_e32 v32, 16, v84
	v_and_b32_e32 v33, 0xffff0000, v84
	v_lshlrev_b32_e32 v34, 16, v85
	v_and_b32_e32 v35, 0xffff0000, v85
	v_lshlrev_b32_e32 v36, 16, v86
	v_and_b32_e32 v37, 0xffff0000, v86
	v_lshlrev_b32_e32 v38, 16, v87
	v_and_b32_e32 v39, 0xffff0000, v87
	v_lshlrev_b32_e32 v40, 16, v88
	v_and_b32_e32 v41, 0xffff0000, v88
	v_lshlrev_b32_e32 v42, 16, v89
	v_and_b32_e32 v43, 0xffff0000, v89
	v_lshlrev_b32_e32 v44, 16, v90
	v_and_b32_e32 v45, 0xffff0000, v90
	v_lshlrev_b32_e32 v46, 16, v91
	v_and_b32_e32 v47, 0xffff0000, v91
	v_cmp_eq_u32_e32 vcc, 0, v116
	s_cbranch_vccz .Lc3_commonB
	v_cmp_ne_u32_e32 vcc, 0, v116
	s_nop 1
	v_cndmask_b32_e32 v16, 0, v16, vcc
	v_cndmask_b32_e32 v17, 0, v17, vcc
	v_cndmask_b32_e32 v18, 0, v18, vcc
	v_cndmask_b32_e32 v19, 0, v19, vcc
	v_cndmask_b32_e32 v20, 0, v20, vcc
	v_cndmask_b32_e32 v21, 0, v21, vcc
	v_cndmask_b32_e32 v22, 0, v22, vcc
	v_cndmask_b32_e32 v23, 0, v23, vcc
	v_cndmask_b32_e32 v24, 0, v24, vcc
	v_cndmask_b32_e32 v25, 0, v25, vcc
	v_cndmask_b32_e32 v26, 0, v26, vcc
	v_cndmask_b32_e32 v27, 0, v27, vcc
	v_cndmask_b32_e32 v28, 0, v28, vcc
	v_cndmask_b32_e32 v29, 0, v29, vcc
	v_cndmask_b32_e32 v30, 0, v30, vcc
	v_cndmask_b32_e32 v31, 0, v31, vcc
	v_cndmask_b32_e32 v48, 0, v48, vcc
	v_cndmask_b32_e32 v49, 0, v49, vcc
	v_cndmask_b32_e32 v50, 0, v50, vcc
	v_cndmask_b32_e32 v51, 0, v51, vcc
	v_cndmask_b32_e32 v52, 0, v52, vcc
	v_cndmask_b32_e32 v53, 0, v53, vcc
	v_cndmask_b32_e32 v54, 0, v54, vcc
	v_cndmask_b32_e32 v55, 0, v55, vcc
	v_cndmask_b32_e32 v56, 0, v56, vcc
	v_cndmask_b32_e32 v57, 0, v57, vcc
	v_cndmask_b32_e32 v58, 0, v58, vcc
	v_cndmask_b32_e32 v59, 0, v59, vcc
	v_cndmask_b32_e32 v60, 0, v60, vcc
	v_cndmask_b32_e32 v61, 0, v61, vcc
	v_cndmask_b32_e32 v62, 0, v62, vcc
	v_cndmask_b32_e32 v63, 0, v63, vcc
.Lc3_commonB:
	v_pk_fma_f32 v[68:69], v[164:165], v[0:1], v[172:173]
	v_pk_fma_f32 v[70:71], v[166:167], v[2:3], v[174:175]
	v_pk_fma_f32 v[72:73], v[168:169], v[4:5], v[176:177]
	v_pk_fma_f32 v[74:75], v[170:171], v[6:7], v[178:179]
	v_pk_fma_f32 v[68:69], v[156:157], v[24:25], v[68:69]
	v_pk_fma_f32 v[70:71], v[158:159], v[26:27], v[70:71]
	v_pk_fma_f32 v[72:73], v[160:161], v[28:29], v[72:73]
	v_pk_fma_f32 v[74:75], v[162:163], v[30:31], v[74:75]
	v_pk_fma_f32 v[68:69], v[148:149], v[16:17], v[68:69]
	v_pk_fma_f32 v[70:71], v[150:151], v[18:19], v[70:71]
	v_pk_fma_f32 v[72:73], v[152:153], v[20:21], v[72:73]
	v_pk_fma_f32 v[74:75], v[154:155], v[22:23], v[74:75]
	v_pk_fma_f32 v[76:77], v[164:165], v[8:9], v[172:173]
	v_pk_fma_f32 v[78:79], v[166:167], v[10:11], v[174:175]
	v_pk_fma_f32 v[80:81], v[168:169], v[12:13], v[176:177]
	v_pk_fma_f32 v[82:83], v[170:171], v[14:15], v[178:179]
	v_pk_fma_f32 v[76:77], v[156:157], v[0:1], v[76:77]
	v_pk_fma_f32 v[78:79], v[158:159], v[2:3], v[78:79]
	v_pk_fma_f32 v[80:81], v[160:161], v[4:5], v[80:81]
	v_pk_fma_f32 v[82:83], v[162:163], v[6:7], v[82:83]
	v_pk_fma_f32 v[76:77], v[148:149], v[24:25], v[76:77]
	v_pk_fma_f32 v[78:79], v[150:151], v[26:27], v[78:79]
	v_pk_fma_f32 v[80:81], v[152:153], v[28:29], v[80:81]
	v_pk_fma_f32 v[82:83], v[154:155], v[30:31], v[82:83]
	v_pk_mul_f32 v[100:101], v[68:69], v[68:69]
	v_pk_mul_f32 v[102:103], v[70:71], v[70:71]
	v_pk_mul_f32 v[104:105], v[72:73], v[72:73]
	v_pk_mul_f32 v[106:107], v[74:75], v[74:75]
	v_pk_mul_f32 v[108:109], v[76:77], v[76:77]
	v_pk_mul_f32 v[110:111], v[78:79], v[78:79]
	v_pk_mul_f32 v[112:113], v[80:81], v[80:81]
	v_pk_mul_f32 v[114:115], v[82:83], v[82:83]
	v_pk_fma_f32 v[100:101], v[100:101], v[218:219], v[220:221]
	v_pk_fma_f32 v[102:103], v[102:103], v[218:219], v[220:221]
	v_pk_fma_f32 v[104:105], v[104:105], v[218:219], v[220:221]
	v_pk_fma_f32 v[106:107], v[106:107], v[218:219], v[220:221]
	v_pk_fma_f32 v[108:109], v[108:109], v[218:219], v[220:221]
	v_pk_fma_f32 v[110:111], v[110:111], v[218:219], v[220:221]
	v_pk_fma_f32 v[112:113], v[112:113], v[218:219], v[220:221]
	v_pk_fma_f32 v[114:115], v[114:115], v[218:219], v[220:221]
	v_pk_mul_f32 v[100:101], v[68:69], v[100:101]
	v_pk_mul_f32 v[102:103], v[70:71], v[102:103]
	v_pk_mul_f32 v[104:105], v[72:73], v[104:105]
	v_pk_mul_f32 v[106:107], v[74:75], v[106:107]
	v_pk_mul_f32 v[108:109], v[76:77], v[108:109]
	v_pk_mul_f32 v[110:111], v[78:79], v[110:111]
	v_pk_mul_f32 v[112:113], v[80:81], v[112:113]
	v_pk_mul_f32 v[114:115], v[82:83], v[114:115]
	v_exp_f32_e32 v100, v100
	v_exp_f32_e32 v101, v101
	v_exp_f32_e32 v102, v102
	v_exp_f32_e32 v103, v103
	v_exp_f32_e32 v104, v104
	v_exp_f32_e32 v105, v105
	v_exp_f32_e32 v106, v106
	v_exp_f32_e32 v107, v107
	v_exp_f32_e32 v108, v108
	v_exp_f32_e32 v109, v109
	v_exp_f32_e32 v110, v110
	v_exp_f32_e32 v111, v111
	v_exp_f32_e32 v112, v112
	v_exp_f32_e32 v113, v113
	v_exp_f32_e32 v114, v114
	v_exp_f32_e32 v115, v115
	v_pk_fma_f32 v[84:85], v[200:201], v[32:33], v[208:209]
	v_pk_fma_f32 v[86:87], v[202:203], v[34:35], v[210:211]
	v_pk_fma_f32 v[88:89], v[204:205], v[36:37], v[212:213]
	v_pk_fma_f32 v[90:91], v[206:207], v[38:39], v[214:215]
	v_pk_fma_f32 v[84:85], v[192:193], v[56:57], v[84:85]
	v_pk_fma_f32 v[86:87], v[194:195], v[58:59], v[86:87]
	v_pk_fma_f32 v[88:89], v[196:197], v[60:61], v[88:89]
	v_pk_fma_f32 v[90:91], v[198:199], v[62:63], v[90:91]
	v_pk_fma_f32 v[84:85], v[180:181], v[48:49], v[84:85]
	v_pk_fma_f32 v[86:87], v[182:183], v[50:51], v[86:87]
	v_pk_fma_f32 v[88:89], v[184:185], v[52:53], v[88:89]
	v_pk_fma_f32 v[90:91], v[186:187], v[54:55], v[90:91]
	v_pk_fma_f32 v[92:93], v[200:201], v[40:41], v[208:209]
	v_pk_fma_f32 v[94:95], v[202:203], v[42:43], v[210:211]
	v_pk_fma_f32 v[96:97], v[204:205], v[44:45], v[212:213]
	v_pk_fma_f32 v[98:99], v[206:207], v[46:47], v[214:215]
	v_pk_fma_f32 v[92:93], v[192:193], v[32:33], v[92:93]
	v_pk_fma_f32 v[94:95], v[194:195], v[34:35], v[94:95]
	v_pk_fma_f32 v[96:97], v[196:197], v[36:37], v[96:97]
	v_pk_fma_f32 v[98:99], v[198:199], v[38:39], v[98:99]
	v_pk_fma_f32 v[92:93], v[180:181], v[56:57], v[92:93]
	v_pk_fma_f32 v[94:95], v[182:183], v[58:59], v[94:95]
	v_pk_fma_f32 v[96:97], v[184:185], v[60:61], v[96:97]
	v_pk_fma_f32 v[98:99], v[186:187], v[62:63], v[98:99]
	v_pk_add_f32 v[100:101], v[100:101], 1.0 op_sel_hi:[1,0]
	v_pk_add_f32 v[102:103], v[102:103], 1.0 op_sel_hi:[1,0]
	v_pk_add_f32 v[104:105], v[104:105], 1.0 op_sel_hi:[1,0]
	v_pk_add_f32 v[106:107], v[106:107], 1.0 op_sel_hi:[1,0]
	v_pk_add_f32 v[108:109], v[108:109], 1.0 op_sel_hi:[1,0]
	v_pk_add_f32 v[110:111], v[110:111], 1.0 op_sel_hi:[1,0]
	v_pk_add_f32 v[112:113], v[112:113], 1.0 op_sel_hi:[1,0]
	v_pk_add_f32 v[114:115], v[114:115], 1.0 op_sel_hi:[1,0]
	v_rcp_f32_e32 v100, v100
	v_rcp_f32_e32 v101, v101
	v_rcp_f32_e32 v102, v102
	v_rcp_f32_e32 v103, v103
	v_rcp_f32_e32 v104, v104
	v_rcp_f32_e32 v105, v105
	v_rcp_f32_e32 v106, v106
	v_rcp_f32_e32 v107, v107
	v_rcp_f32_e32 v108, v108
	v_rcp_f32_e32 v109, v109
	v_rcp_f32_e32 v110, v110
	v_rcp_f32_e32 v111, v111
	v_rcp_f32_e32 v112, v112
	v_rcp_f32_e32 v113, v113
	v_rcp_f32_e32 v114, v114
	v_rcp_f32_e32 v115, v115
	v_add_u32_e32 v117, 1, v67
	v_mad_i64_i32 v[124:125], s[4:5], v67, s56, v[64:65]
	v_mad_i64_i32 v[126:127], s[4:5], v117, s56, v[64:65]
	v_pk_mul_f32 v[68:69], v[68:69], v[100:101]
	v_pk_mul_f32 v[70:71], v[70:71], v[102:103]
	v_pk_mul_f32 v[72:73], v[72:73], v[104:105]
	v_pk_mul_f32 v[74:75], v[74:75], v[106:107]
	v_pk_mul_f32 v[76:77], v[76:77], v[108:109]
	v_pk_mul_f32 v[78:79], v[78:79], v[110:111]
	v_pk_mul_f32 v[80:81], v[80:81], v[112:113]
	v_pk_mul_f32 v[82:83], v[82:83], v[114:115]
	v_pk_mul_f32 v[68:69], v[68:69], v[84:85]
	v_pk_mul_f32 v[70:71], v[70:71], v[86:87]
	v_pk_mul_f32 v[72:73], v[72:73], v[88:89]
	v_pk_mul_f32 v[74:75], v[74:75], v[90:91]
	v_pk_mul_f32 v[76:77], v[76:77], v[92:93]
	v_pk_mul_f32 v[78:79], v[78:79], v[94:95]
	v_pk_mul_f32 v[80:81], v[80:81], v[96:97]
	v_pk_mul_f32 v[82:83], v[82:83], v[98:99]
	v_cvt_pk_bf16_f32 v116, v68, v69
	v_cvt_pk_bf16_f32 v117, v70, v71
	v_cvt_pk_bf16_f32 v118, v72, v73
	v_cvt_pk_bf16_f32 v119, v74, v75
	v_cvt_pk_bf16_f32 v120, v76, v77
	v_cvt_pk_bf16_f32 v121, v78, v79
	v_cvt_pk_bf16_f32 v122, v80, v81
	v_cvt_pk_bf16_f32 v123, v82, v83
	s_mov_b64 s[4:5], exec
	s_and_b64 exec, exec, s[0:1]
	global_store_dwordx4 v[124:125], v[116:119], off
	global_store_dwordx4 v[126:127], v[120:123], off
	s_mov_b64 exec, s[4:5]
	v_add_u32_e32 v66, 2, v66
	v_add_u32_e32 v222, 0x840, v222
	s_add_i32 s11, s11, 1
	s_cmp_lg_u32 s11, 2
	s_cbranch_scc1 .Lc3_loop
	s_branch .LBB0_1022
